# k10 + the two MMA blocks of each segment interleaved so 4 consecutive MFMAs share the A operand (accumulators strictly descending); same bytes
# baseline (speedup 1.0000x reference)
.LBB0_165:
	v_add_u32_e32 v1, 0x10000, v245
	ds_read_b128 v[148:151], v1
	ds_read_b128 v[152:155], v1 offset:1024
	ds_read_b128 v[156:159], v1 offset:2048
	ds_read_b128 v[160:163], v1 offset:3072
	v_add_u32_e32 v1, 0x14000, v245
	ds_read_b128 v[132:135], v1
	ds_read_b128 v[136:139], v1 offset:1024
	ds_read_b128 v[140:143], v1 offset:2048
	ds_read_b128 v[144:147], v1 offset:3072
	v_lshl_add_u64 v[2:3], v[224:225], 0, s[0:1]
	s_add_i32 m0, s77, 0xc000
	s_waitcnt lgkmcnt(0)
	ds_read_b128 v[176:179], v246
	ds_read_b128 v[192:195], v246 offset:1024
	ds_read_b128 v[172:175], v246 offset:2048
	ds_read_b128 v[188:191], v246 offset:3072
	ds_read_b128 v[168:171], v246 offset:4096
	ds_read_b128 v[184:187], v246 offset:5120
	ds_read_b128 v[164:167], v246 offset:6144
	ds_read_b128 v[180:183], v246 offset:7168
	global_load_lds_dwordx4 v[2:3], off
	v_lshl_add_u64 v[2:3], v[222:223], 0, s[0:1]
	s_add_i32 m0, s77, 0xe000
	s_nop 0
	global_load_lds_dwordx4 v[2:3], off
	s_waitcnt vmcnt(8)
	s_waitcnt lgkmcnt(0)
	s_barrier
	s_setprio 1
	s_waitcnt lgkmcnt(0)
	v_mfma_f32_16x16x32_bf16 v[128:131], v[148:151], v[176:179], v[128:131]
	v_mfma_f32_16x16x32_bf16 v[124:127], v[156:159], v[176:179], v[124:127]
	v_mfma_f32_16x16x32_bf16 v[120:123], v[132:135], v[176:179], v[120:123]
	v_mfma_f32_16x16x32_bf16 v[116:119], v[140:143], v[176:179], v[116:119]
	v_mfma_f32_16x16x32_bf16 v[112:115], v[148:151], v[172:175], v[112:115]
	v_mfma_f32_16x16x32_bf16 v[108:111], v[156:159], v[172:175], v[108:111]
	v_mfma_f32_16x16x32_bf16 v[104:107], v[132:135], v[172:175], v[104:107]
	v_mfma_f32_16x16x32_bf16 v[100:103], v[140:143], v[172:175], v[100:103]
	v_mfma_f32_16x16x32_bf16 v[96:99], v[148:151], v[168:171], v[96:99]
	v_mfma_f32_16x16x32_bf16 v[92:95], v[156:159], v[168:171], v[92:95]
	v_mfma_f32_16x16x32_bf16 v[88:91], v[132:135], v[168:171], v[88:91]
	v_mfma_f32_16x16x32_bf16 v[84:87], v[140:143], v[168:171], v[84:87]
	v_mfma_f32_16x16x32_bf16 v[80:83], v[148:151], v[164:167], v[80:83]
	v_mfma_f32_16x16x32_bf16 v[76:79], v[156:159], v[164:167], v[76:79]
	v_mfma_f32_16x16x32_bf16 v[72:75], v[132:135], v[164:167], v[72:75]
	v_mfma_f32_16x16x32_bf16 v[68:71], v[140:143], v[164:167], v[68:71]
	s_setprio 0
	s_setprio 1
	v_mfma_f32_16x16x32_bf16 v[128:131], v[152:155], v[192:195], v[128:131]
	v_mfma_f32_16x16x32_bf16 v[124:127], v[160:163], v[192:195], v[124:127]
	v_mfma_f32_16x16x32_bf16 v[120:123], v[136:139], v[192:195], v[120:123]
	v_mfma_f32_16x16x32_bf16 v[116:119], v[144:147], v[192:195], v[116:119]
	v_mfma_f32_16x16x32_bf16 v[112:115], v[152:155], v[188:191], v[112:115]
	v_mfma_f32_16x16x32_bf16 v[108:111], v[160:163], v[188:191], v[108:111]
	v_mfma_f32_16x16x32_bf16 v[104:107], v[136:139], v[188:191], v[104:107]
	v_mfma_f32_16x16x32_bf16 v[100:103], v[144:147], v[188:191], v[100:103]
	v_mfma_f32_16x16x32_bf16 v[96:99], v[152:155], v[184:187], v[96:99]
	v_mfma_f32_16x16x32_bf16 v[92:95], v[160:163], v[184:187], v[92:95]
	v_mfma_f32_16x16x32_bf16 v[88:91], v[136:139], v[184:187], v[88:91]
	v_mfma_f32_16x16x32_bf16 v[84:87], v[144:147], v[184:187], v[84:87]
	v_mfma_f32_16x16x32_bf16 v[80:83], v[152:155], v[180:183], v[80:83]
	v_mfma_f32_16x16x32_bf16 v[76:79], v[160:163], v[180:183], v[76:79]
	v_mfma_f32_16x16x32_bf16 v[72:75], v[136:139], v[180:183], v[72:75]
	v_mfma_f32_16x16x32_bf16 v[68:71], v[144:147], v[180:183], v[68:71]
	s_setprio 0
	s_barrier
	v_cndmask_b32_e64 v1, 0, 1, s[20:21]
	v_cmp_ne_u32_e64 s[44:45], 1, v1
	s_andn2_b64 vcc, exec, s[20:21]
	s_cbranch_vccnz .LBB0_167
	ds_read_b128 v[176:179], v246 offset:16384
	ds_read_b128 v[192:195], v246 offset:17408
	ds_read_b128 v[172:175], v246 offset:18432
	ds_read_b128 v[188:191], v246 offset:19456
	ds_read_b128 v[168:171], v246 offset:20480
	ds_read_b128 v[184:187], v246 offset:21504
	ds_read_b128 v[164:167], v246 offset:22528
	ds_read_b128 v[180:183], v246 offset:23552
.LBB0_167:
	s_add_u32 s26, s6, s0
	s_addc_u32 s27, s7, s1
	s_add_u32 s66, s26, 0x100
	s_addc_u32 s67, s27, 0
	s_add_u32 vcc_lo, s69, s0
	s_addc_u32 vcc_hi, s70, s1
	s_cmpk_eq_i32 s0, 0xf00
	s_cselect_b64 s[26:27], -1, 0
	s_and_b64 s[48:49], s[26:27], exec
	s_cselect_b32 s49, s29, vcc_hi
	s_cselect_b32 s48, s68, vcc_lo
	s_mov_b32 m0, s80
	s_cselect_b32 s67, s5, s67
	s_cselect_b32 s66, s47, s66
	v_lshl_add_u64 v[2:3], s[48:49], 0, v[210:211]
	s_add_u32 vcc_lo, s48, 0x80000
	global_load_lds_dwordx4 v[2:3], off
	v_lshl_add_u64 v[226:227], s[48:49], 0, v[214:215]
	s_mov_b32 m0, s81
	s_addc_u32 vcc_hi, s49, 0
	global_load_lds_dwordx4 v[226:227], off
	v_lshl_add_u64 v[196:197], vcc, 0, v[210:211]
	s_mov_b32 m0, s82
	v_lshl_add_u64 v[228:229], s[66:67], 0, v[208:209]
	global_load_lds_dwordx4 v[196:197], off
	v_lshl_add_u64 v[196:197], vcc, 0, v[214:215]
	s_mov_b32 m0, s83
	v_lshl_add_u64 v[230:231], s[66:67], 0, v[212:213]
	global_load_lds_dwordx4 v[196:197], off
	s_mov_b32 m0, s77
	s_and_b64 vcc, exec, s[44:45]
	global_load_lds_dwordx4 v[228:229], off
	s_mov_b32 m0, s84
	s_nop 0
	global_load_lds_dwordx4 v[230:231], off
	s_waitcnt vmcnt(8)
	s_waitcnt lgkmcnt(0)
	s_cbranch_vccnz .Lskp_p1
	s_barrier
	s_setprio 1
	s_waitcnt lgkmcnt(0)
	v_mfma_f32_16x16x32_bf16 v[64:67], v[148:151], v[176:179], v[64:67]
	v_mfma_f32_16x16x32_bf16 v[60:63], v[156:159], v[176:179], v[60:63]
	v_mfma_f32_16x16x32_bf16 v[56:59], v[132:135], v[176:179], v[56:59]
	v_mfma_f32_16x16x32_bf16 v[52:55], v[140:143], v[176:179], v[52:55]
	v_mfma_f32_16x16x32_bf16 v[48:51], v[148:151], v[172:175], v[48:51]
	v_mfma_f32_16x16x32_bf16 v[44:47], v[156:159], v[172:175], v[44:47]
	v_mfma_f32_16x16x32_bf16 v[40:43], v[132:135], v[172:175], v[40:43]
	v_mfma_f32_16x16x32_bf16 v[36:39], v[140:143], v[172:175], v[36:39]
	v_mfma_f32_16x16x32_bf16 v[32:35], v[148:151], v[168:171], v[32:35]
	v_mfma_f32_16x16x32_bf16 v[28:31], v[156:159], v[168:171], v[28:31]
	v_mfma_f32_16x16x32_bf16 v[24:27], v[132:135], v[168:171], v[24:27]
	v_mfma_f32_16x16x32_bf16 v[20:23], v[140:143], v[168:171], v[20:23]
	v_mfma_f32_16x16x32_bf16 v[16:19], v[148:151], v[164:167], v[16:19]
	v_mfma_f32_16x16x32_bf16 v[12:15], v[156:159], v[164:167], v[12:15]
	v_mfma_f32_16x16x32_bf16 v[8:11], v[132:135], v[164:167], v[8:11]
	v_mfma_f32_16x16x32_bf16 v[4:7], v[140:143], v[164:167], v[4:7]
	s_setprio 0
	s_setprio 1
	v_mfma_f32_16x16x32_bf16 v[64:67], v[152:155], v[192:195], v[64:67]
	v_mfma_f32_16x16x32_bf16 v[60:63], v[160:163], v[192:195], v[60:63]
	v_mfma_f32_16x16x32_bf16 v[56:59], v[136:139], v[192:195], v[56:59]
	v_mfma_f32_16x16x32_bf16 v[52:55], v[144:147], v[192:195], v[52:55]
	v_mfma_f32_16x16x32_bf16 v[48:51], v[152:155], v[188:191], v[48:51]
	v_mfma_f32_16x16x32_bf16 v[44:47], v[160:163], v[188:191], v[44:47]
	v_mfma_f32_16x16x32_bf16 v[40:43], v[136:139], v[188:191], v[40:43]
	v_mfma_f32_16x16x32_bf16 v[36:39], v[144:147], v[188:191], v[36:39]
	v_mfma_f32_16x16x32_bf16 v[32:35], v[152:155], v[184:187], v[32:35]
	v_mfma_f32_16x16x32_bf16 v[28:31], v[160:163], v[184:187], v[28:31]
	v_mfma_f32_16x16x32_bf16 v[24:27], v[136:139], v[184:187], v[24:27]
	v_mfma_f32_16x16x32_bf16 v[20:23], v[144:147], v[184:187], v[20:23]
	v_mfma_f32_16x16x32_bf16 v[16:19], v[152:155], v[180:183], v[16:19]
	v_mfma_f32_16x16x32_bf16 v[12:15], v[160:163], v[180:183], v[12:15]
	v_mfma_f32_16x16x32_bf16 v[8:11], v[136:139], v[180:183], v[8:11]
	v_mfma_f32_16x16x32_bf16 v[4:7], v[144:147], v[180:183], v[4:7]
	s_setprio 0
.LBB0_169:
	s_barrier
	v_add_u32_e32 v1, 0x18000, v245
	ds_read_b128 v[148:151], v1
	ds_read_b128 v[152:155], v1 offset:1024
	ds_read_b128 v[156:159], v1 offset:2048
	ds_read_b128 v[160:163], v1 offset:3072
	v_add_u32_e32 v1, 0x1c000, v245
	ds_read_b128 v[132:135], v1
	ds_read_b128 v[136:139], v1 offset:1024
	ds_read_b128 v[140:143], v1 offset:2048
	ds_read_b128 v[144:147], v1 offset:3072
	s_and_b64 s[26:27], s[42:43], s[26:27]
	s_and_b64 s[26:27], s[26:27], exec
	s_cselect_b32 s26, s52, s50
	s_cselect_b32 s27, 0, s51
	s_add_u32 s26, s66, s26
	s_addc_u32 s27, s67, s27
	s_mov_b32 m0, s85
	v_lshl_add_u64 v[196:197], s[26:27], 0, v[208:209]
	s_waitcnt lgkmcnt(0)
	ds_read_b128 v[176:179], v246 offset:32768
	ds_read_b128 v[192:195], v246 offset:33792
	ds_read_b128 v[172:175], v246 offset:34816
	ds_read_b128 v[188:191], v246 offset:35840
	ds_read_b128 v[168:171], v246 offset:36864
	ds_read_b128 v[184:187], v246 offset:37888
	ds_read_b128 v[164:167], v246 offset:38912
	ds_read_b128 v[180:183], v246 offset:39936
	global_load_lds_dwordx4 v[196:197], off
	v_lshl_add_u64 v[196:197], s[26:27], 0, v[212:213]
	s_mov_b32 m0, s86
	s_nop 0
	global_load_lds_dwordx4 v[196:197], off
	s_waitcnt vmcnt(8)
	s_waitcnt lgkmcnt(0)
	s_barrier
	s_setprio 1
	s_waitcnt lgkmcnt(0)
	v_mfma_f32_16x16x32_bf16 v[128:131], v[148:151], v[176:179], v[128:131]
	v_mfma_f32_16x16x32_bf16 v[124:127], v[156:159], v[176:179], v[124:127]
	v_mfma_f32_16x16x32_bf16 v[120:123], v[132:135], v[176:179], v[120:123]
	v_mfma_f32_16x16x32_bf16 v[116:119], v[140:143], v[176:179], v[116:119]
	v_mfma_f32_16x16x32_bf16 v[112:115], v[148:151], v[172:175], v[112:115]
	v_mfma_f32_16x16x32_bf16 v[108:111], v[156:159], v[172:175], v[108:111]
	v_mfma_f32_16x16x32_bf16 v[104:107], v[132:135], v[172:175], v[104:107]
	v_mfma_f32_16x16x32_bf16 v[100:103], v[140:143], v[172:175], v[100:103]
	v_mfma_f32_16x16x32_bf16 v[96:99], v[148:151], v[168:171], v[96:99]
	v_mfma_f32_16x16x32_bf16 v[92:95], v[156:159], v[168:171], v[92:95]
	v_mfma_f32_16x16x32_bf16 v[88:91], v[132:135], v[168:171], v[88:91]
	v_mfma_f32_16x16x32_bf16 v[84:87], v[140:143], v[168:171], v[84:87]
	v_mfma_f32_16x16x32_bf16 v[80:83], v[148:151], v[164:167], v[80:83]
	v_mfma_f32_16x16x32_bf16 v[76:79], v[156:159], v[164:167], v[76:79]
	v_mfma_f32_16x16x32_bf16 v[72:75], v[132:135], v[164:167], v[72:75]
	v_mfma_f32_16x16x32_bf16 v[68:71], v[140:143], v[164:167], v[68:71]
	s_setprio 0
	s_setprio 1
	v_mfma_f32_16x16x32_bf16 v[128:131], v[152:155], v[192:195], v[128:131]
	v_mfma_f32_16x16x32_bf16 v[124:127], v[160:163], v[192:195], v[124:127]
	v_mfma_f32_16x16x32_bf16 v[120:123], v[136:139], v[192:195], v[120:123]
	v_mfma_f32_16x16x32_bf16 v[116:119], v[144:147], v[192:195], v[116:119]
	v_mfma_f32_16x16x32_bf16 v[112:115], v[152:155], v[188:191], v[112:115]
	v_mfma_f32_16x16x32_bf16 v[108:111], v[160:163], v[188:191], v[108:111]
	v_mfma_f32_16x16x32_bf16 v[104:107], v[136:139], v[188:191], v[104:107]
	v_mfma_f32_16x16x32_bf16 v[100:103], v[144:147], v[188:191], v[100:103]
	v_mfma_f32_16x16x32_bf16 v[96:99], v[152:155], v[184:187], v[96:99]
	v_mfma_f32_16x16x32_bf16 v[92:95], v[160:163], v[184:187], v[92:95]
	v_mfma_f32_16x16x32_bf16 v[88:91], v[136:139], v[184:187], v[88:91]
	v_mfma_f32_16x16x32_bf16 v[84:87], v[144:147], v[184:187], v[84:87]
	v_mfma_f32_16x16x32_bf16 v[80:83], v[152:155], v[180:183], v[80:83]
	v_mfma_f32_16x16x32_bf16 v[76:79], v[160:163], v[180:183], v[76:79]
	v_mfma_f32_16x16x32_bf16 v[72:75], v[136:139], v[180:183], v[72:75]
	v_mfma_f32_16x16x32_bf16 v[68:71], v[144:147], v[180:183], v[68:71]
	s_setprio 0
	s_barrier
	s_and_b64 vcc, exec, s[44:45]
	s_cbranch_vccnz .LBB0_171
	ds_read_b128 v[176:179], v246 offset:49152
	ds_read_b128 v[192:195], v246 offset:50176
	ds_read_b128 v[172:175], v246 offset:51200
	ds_read_b128 v[188:191], v246 offset:52224
	ds_read_b128 v[168:171], v246 offset:53248
	ds_read_b128 v[184:187], v246 offset:54272
	ds_read_b128 v[164:167], v246 offset:55296
	ds_read_b128 v[180:183], v246 offset:56320
.LBB0_171:
	s_mov_b32 m0, s58
	v_lshl_add_u64 v[2:3], v[2:3], 0, s[72:73]
	s_add_u32 s26, s48, 0x80080
	global_load_lds_dwordx4 v[2:3], off
	v_lshl_add_u64 v[2:3], v[226:227], 0, s[72:73]
	s_mov_b32 m0, s59
	s_addc_u32 s27, s49, 0
	global_load_lds_dwordx4 v[2:3], off
	v_lshl_add_u64 v[2:3], s[26:27], 0, v[210:211]
	s_mov_b32 m0, s62
	s_and_b64 vcc, exec, s[44:45]
	global_load_lds_dwordx4 v[2:3], off
	v_lshl_add_u64 v[2:3], s[26:27], 0, v[214:215]
	s_mov_b32 m0, s63
	s_nop 0
	global_load_lds_dwordx4 v[2:3], off
	v_lshl_add_u64 v[2:3], v[228:229], 0, s[72:73]
	s_mov_b32 m0, s60
	s_nop 0
	global_load_lds_dwordx4 v[2:3], off
	v_lshl_add_u64 v[2:3], v[230:231], 0, s[72:73]
	s_mov_b32 m0, s61
	s_nop 0
	global_load_lds_dwordx4 v[2:3], off
	s_waitcnt vmcnt(8)
	s_waitcnt lgkmcnt(0)
	s_cbranch_vccnz .Lskp_p2
	s_barrier
	s_setprio 1
	s_waitcnt lgkmcnt(0)
	v_mfma_f32_16x16x32_bf16 v[64:67], v[148:151], v[176:179], v[64:67]
	v_mfma_f32_16x16x32_bf16 v[60:63], v[156:159], v[176:179], v[60:63]
	v_mfma_f32_16x16x32_bf16 v[56:59], v[132:135], v[176:179], v[56:59]
	v_mfma_f32_16x16x32_bf16 v[52:55], v[140:143], v[176:179], v[52:55]
	v_mfma_f32_16x16x32_bf16 v[48:51], v[148:151], v[172:175], v[48:51]
	v_mfma_f32_16x16x32_bf16 v[44:47], v[156:159], v[172:175], v[44:47]
	v_mfma_f32_16x16x32_bf16 v[40:43], v[132:135], v[172:175], v[40:43]
	v_mfma_f32_16x16x32_bf16 v[36:39], v[140:143], v[172:175], v[36:39]
	v_mfma_f32_16x16x32_bf16 v[32:35], v[148:151], v[168:171], v[32:35]
	v_mfma_f32_16x16x32_bf16 v[28:31], v[156:159], v[168:171], v[28:31]
	v_mfma_f32_16x16x32_bf16 v[24:27], v[132:135], v[168:171], v[24:27]
	v_mfma_f32_16x16x32_bf16 v[20:23], v[140:143], v[168:171], v[20:23]
	v_mfma_f32_16x16x32_bf16 v[16:19], v[148:151], v[164:167], v[16:19]
	v_mfma_f32_16x16x32_bf16 v[12:15], v[156:159], v[164:167], v[12:15]
	v_mfma_f32_16x16x32_bf16 v[8:11], v[132:135], v[164:167], v[8:11]
	v_mfma_f32_16x16x32_bf16 v[2:5], v[140:143], v[164:167], v[4:7]
	s_setprio 0
	s_setprio 1
	v_mfma_f32_16x16x32_bf16 v[64:67], v[152:155], v[192:195], v[64:67]
	v_mfma_f32_16x16x32_bf16 v[60:63], v[160:163], v[192:195], v[60:63]
	v_mfma_f32_16x16x32_bf16 v[56:59], v[136:139], v[192:195], v[56:59]
	v_mfma_f32_16x16x32_bf16 v[52:55], v[144:147], v[192:195], v[52:55]
	v_mfma_f32_16x16x32_bf16 v[48:51], v[152:155], v[188:191], v[48:51]
	v_mfma_f32_16x16x32_bf16 v[44:47], v[160:163], v[188:191], v[44:47]
	v_mfma_f32_16x16x32_bf16 v[40:43], v[136:139], v[188:191], v[40:43]
	v_mfma_f32_16x16x32_bf16 v[36:39], v[144:147], v[188:191], v[36:39]
	v_mfma_f32_16x16x32_bf16 v[32:35], v[152:155], v[184:187], v[32:35]
	v_mfma_f32_16x16x32_bf16 v[28:31], v[160:163], v[184:187], v[28:31]
	v_mfma_f32_16x16x32_bf16 v[24:27], v[136:139], v[184:187], v[24:27]
	v_mfma_f32_16x16x32_bf16 v[20:23], v[144:147], v[184:187], v[20:23]
	v_mfma_f32_16x16x32_bf16 v[16:19], v[152:155], v[180:183], v[16:19]
	v_mfma_f32_16x16x32_bf16 v[12:15], v[160:163], v[180:183], v[12:15]
	v_mfma_f32_16x16x32_bf16 v[8:11], v[136:139], v[180:183], v[8:11]
	v_mfma_f32_16x16x32_bf16 v[4:7], v[144:147], v[180:183], v[2:5]
	s_setprio 0

.LBB0_559:
	s_add_u32 s0, s8, 0x100
	s_addc_u32 s1, s9, 0
	s_add_i32 s35, 0, 0x10000
	s_cmp_eq_u32 s34, 28
	s_cselect_b32 s13, s3, s1
	s_cselect_b32 s12, s18, s0
	s_cselect_b32 s11, s19, s33
	s_cselect_b32 s10, s22, s23
	s_add_i32 s36, 0, 0x14000
	v_add_u32_e32 v142, s35, v210
	v_add_u32_e32 v158, s36, v210
	ds_read_b128 v[130:133], v142
	ds_read_b128 v[134:137], v142 offset:1024
	ds_read_b128 v[138:141], v142 offset:2048
	ds_read_b128 v[142:145], v142 offset:3072
	ds_read_b128 v[146:149], v158
	ds_read_b128 v[150:153], v158 offset:1024
	ds_read_b128 v[154:157], v158 offset:2048
	ds_read_b128 v[158:161], v158 offset:3072
	v_lshl_add_u64 v[198:199], s[8:9], 0, v[190:191]
	s_add_i32 m0, s21, 0xc000
	ds_read_b128 v[162:165], v220
	ds_read_b128 v[166:169], v220 offset:1024
	ds_read_b128 v[170:173], v220 offset:2048
	ds_read_b128 v[174:177], v220 offset:3072
	ds_read_b128 v[178:181], v220 offset:4096
	ds_read_b128 v[182:185], v220 offset:5120
	ds_read_b128 v[194:197], v220 offset:6144
	ds_read_b128 v[222:225], v220 offset:7168
	global_load_lds_dwordx4 v[198:199], off
	v_lshl_add_u64 v[198:199], s[8:9], 0, v[192:193]
	s_add_i32 m0, s21, 0xe000
	s_nop 0
	global_load_lds_dwordx4 v[198:199], off
	s_waitcnt vmcnt(8)
	s_waitcnt lgkmcnt(0)
	s_barrier
	s_setprio 1
	s_waitcnt lgkmcnt(0)
	v_mfma_f32_16x16x32_bf16 v[126:129], v[130:133], v[162:165], v[126:129]
	v_mfma_f32_16x16x32_bf16 v[122:125], v[138:141], v[162:165], v[122:125]
	v_mfma_f32_16x16x32_bf16 v[118:121], v[146:149], v[162:165], v[118:121]
	v_mfma_f32_16x16x32_bf16 v[114:117], v[154:157], v[162:165], v[114:117]
	v_mfma_f32_16x16x32_bf16 v[110:113], v[130:133], v[170:173], v[110:113]
	v_mfma_f32_16x16x32_bf16 v[106:109], v[138:141], v[170:173], v[106:109]
	v_mfma_f32_16x16x32_bf16 v[102:105], v[146:149], v[170:173], v[102:105]
	v_mfma_f32_16x16x32_bf16 v[98:101], v[154:157], v[170:173], v[98:101]
	v_mfma_f32_16x16x32_bf16 v[94:97], v[130:133], v[178:181], v[94:97]
	v_mfma_f32_16x16x32_bf16 v[90:93], v[138:141], v[178:181], v[90:93]
	v_mfma_f32_16x16x32_bf16 v[86:89], v[146:149], v[178:181], v[86:89]
	v_mfma_f32_16x16x32_bf16 v[82:85], v[154:157], v[178:181], v[82:85]
	v_mfma_f32_16x16x32_bf16 v[78:81], v[130:133], v[194:197], v[78:81]
	v_mfma_f32_16x16x32_bf16 v[74:77], v[138:141], v[194:197], v[74:77]
	v_mfma_f32_16x16x32_bf16 v[70:73], v[146:149], v[194:197], v[70:73]
	v_mfma_f32_16x16x32_bf16 v[66:69], v[154:157], v[194:197], v[66:69]
	s_setprio 0
	s_setprio 1
	v_mfma_f32_16x16x32_bf16 v[126:129], v[134:137], v[166:169], v[126:129]
	v_mfma_f32_16x16x32_bf16 v[122:125], v[142:145], v[166:169], v[122:125]
	v_mfma_f32_16x16x32_bf16 v[118:121], v[150:153], v[166:169], v[118:121]
	v_mfma_f32_16x16x32_bf16 v[114:117], v[158:161], v[166:169], v[114:117]
	v_mfma_f32_16x16x32_bf16 v[110:113], v[134:137], v[174:177], v[110:113]
	v_mfma_f32_16x16x32_bf16 v[106:109], v[142:145], v[174:177], v[106:109]
	v_mfma_f32_16x16x32_bf16 v[102:105], v[150:153], v[174:177], v[102:105]
	v_mfma_f32_16x16x32_bf16 v[98:101], v[158:161], v[174:177], v[98:101]
	v_mfma_f32_16x16x32_bf16 v[94:97], v[134:137], v[182:185], v[94:97]
	v_mfma_f32_16x16x32_bf16 v[90:93], v[142:145], v[182:185], v[90:93]
	v_mfma_f32_16x16x32_bf16 v[86:89], v[150:153], v[182:185], v[86:89]
	v_mfma_f32_16x16x32_bf16 v[82:85], v[158:161], v[182:185], v[82:85]
	v_mfma_f32_16x16x32_bf16 v[78:81], v[134:137], v[222:225], v[78:81]
	v_mfma_f32_16x16x32_bf16 v[74:77], v[142:145], v[222:225], v[74:77]
	v_mfma_f32_16x16x32_bf16 v[70:73], v[150:153], v[222:225], v[70:73]
	v_mfma_f32_16x16x32_bf16 v[66:69], v[158:161], v[222:225], v[66:69]
	s_setprio 0
	s_barrier
	s_add_i32 s8, s35, s14
	v_lshl_add_u64 v[198:199], s[10:11], 0, v[188:189]
	s_mov_b32 m0, s8
	ds_read_b128 v[162:165], v220 offset:16384
	ds_read_b128 v[166:169], v220 offset:17408
	ds_read_b128 v[170:173], v220 offset:18432
	ds_read_b128 v[174:177], v220 offset:19456
	ds_read_b128 v[178:181], v220 offset:20480
	ds_read_b128 v[182:185], v220 offset:21504
	ds_read_b128 v[194:197], v220 offset:22528
	ds_read_b128 v[222:225], v220 offset:23552
	global_load_lds_dwordx4 v[198:199], off
	s_add_i32 m0, s8, 0x2000
	s_add_u32 s8, s10, 0x80000
	v_lshl_add_u64 v[208:209], s[10:11], 0, v[186:187]
	s_addc_u32 s9, s11, 0
	s_add_i32 s35, s36, s14
	global_load_lds_dwordx4 v[208:209], off
	v_lshl_add_u64 v[226:227], s[8:9], 0, v[188:189]
	s_mov_b32 m0, s35
	v_lshl_add_u64 v[228:229], s[12:13], 0, v[186:187]
	global_load_lds_dwordx4 v[226:227], off
	v_lshl_add_u64 v[226:227], s[8:9], 0, v[186:187]
	s_add_i32 m0, s35, 0x2000
	s_nop 0
	global_load_lds_dwordx4 v[226:227], off
	v_lshl_add_u64 v[226:227], s[12:13], 0, v[188:189]
	s_mov_b32 m0, s21
	s_nop 0
	global_load_lds_dwordx4 v[226:227], off
	s_mov_b32 m0, s26
	s_nop 0
	global_load_lds_dwordx4 v[228:229], off
	s_waitcnt vmcnt(8)
	s_waitcnt lgkmcnt(0)
	s_barrier
	s_setprio 1
	s_waitcnt lgkmcnt(0)
	v_mfma_f32_16x16x32_bf16 v[62:65], v[130:133], v[162:165], v[62:65]
	v_mfma_f32_16x16x32_bf16 v[58:61], v[138:141], v[162:165], v[58:61]
	v_mfma_f32_16x16x32_bf16 v[54:57], v[146:149], v[162:165], v[54:57]
	v_mfma_f32_16x16x32_bf16 v[50:53], v[154:157], v[162:165], v[50:53]
	v_mfma_f32_16x16x32_bf16 v[46:49], v[130:133], v[170:173], v[46:49]
	v_mfma_f32_16x16x32_bf16 v[42:45], v[138:141], v[170:173], v[42:45]
	v_mfma_f32_16x16x32_bf16 v[38:41], v[146:149], v[170:173], v[38:41]
	v_mfma_f32_16x16x32_bf16 v[34:37], v[154:157], v[170:173], v[34:37]
	v_mfma_f32_16x16x32_bf16 v[30:33], v[130:133], v[178:181], v[30:33]
	v_mfma_f32_16x16x32_bf16 v[26:29], v[138:141], v[178:181], v[26:29]
	v_mfma_f32_16x16x32_bf16 v[22:25], v[146:149], v[178:181], v[22:25]
	v_mfma_f32_16x16x32_bf16 v[18:21], v[154:157], v[178:181], v[18:21]
	v_mfma_f32_16x16x32_bf16 v[14:17], v[130:133], v[194:197], v[14:17]
	v_mfma_f32_16x16x32_bf16 v[10:13], v[138:141], v[194:197], v[10:13]
	v_mfma_f32_16x16x32_bf16 v[6:9], v[146:149], v[194:197], v[6:9]
	v_mfma_f32_16x16x32_bf16 v[2:5], v[154:157], v[194:197], v[2:5]
	s_setprio 0
	s_setprio 1
	v_mfma_f32_16x16x32_bf16 v[62:65], v[134:137], v[166:169], v[62:65]
	v_mfma_f32_16x16x32_bf16 v[58:61], v[142:145], v[166:169], v[58:61]
	v_mfma_f32_16x16x32_bf16 v[54:57], v[150:153], v[166:169], v[54:57]
	v_mfma_f32_16x16x32_bf16 v[50:53], v[158:161], v[166:169], v[50:53]
	v_mfma_f32_16x16x32_bf16 v[46:49], v[134:137], v[174:177], v[46:49]
	v_mfma_f32_16x16x32_bf16 v[42:45], v[142:145], v[174:177], v[42:45]
	v_mfma_f32_16x16x32_bf16 v[38:41], v[150:153], v[174:177], v[38:41]
	v_mfma_f32_16x16x32_bf16 v[34:37], v[158:161], v[174:177], v[34:37]
	v_mfma_f32_16x16x32_bf16 v[30:33], v[134:137], v[182:185], v[30:33]
	v_mfma_f32_16x16x32_bf16 v[26:29], v[142:145], v[182:185], v[26:29]
	v_mfma_f32_16x16x32_bf16 v[22:25], v[150:153], v[182:185], v[22:25]
	v_mfma_f32_16x16x32_bf16 v[18:21], v[158:161], v[182:185], v[18:21]
	v_mfma_f32_16x16x32_bf16 v[14:17], v[134:137], v[222:225], v[14:17]
	v_mfma_f32_16x16x32_bf16 v[10:13], v[142:145], v[222:225], v[10:13]
	v_mfma_f32_16x16x32_bf16 v[6:9], v[150:153], v[222:225], v[6:9]
	v_mfma_f32_16x16x32_bf16 v[2:5], v[158:161], v[222:225], v[2:5]
	s_setprio 0
	s_barrier
	s_add_i32 s35, 0, 0x18000
	s_add_i32 s36, 0, 0x1c000
	v_add_u32_e32 v142, s35, v210
	v_add_u32_e32 v158, s36, v210
	ds_read_b128 v[130:133], v142
	ds_read_b128 v[134:137], v142 offset:1024
	ds_read_b128 v[138:141], v142 offset:2048
	ds_read_b128 v[142:145], v142 offset:3072
	ds_read_b128 v[146:149], v158
	ds_read_b128 v[150:153], v158 offset:1024
	ds_read_b128 v[154:157], v158 offset:2048
	ds_read_b128 v[158:161], v158 offset:3072
	s_add_u32 s8, s12, 0x80000
	s_addc_u32 s9, s13, 0
	s_mov_b32 m0, s27
	v_lshl_add_u64 v[230:231], s[8:9], 0, v[188:189]
	ds_read_b128 v[162:165], v220 offset:32768
	ds_read_b128 v[166:169], v220 offset:33792
	ds_read_b128 v[170:173], v220 offset:34816
	ds_read_b128 v[174:177], v220 offset:35840
	ds_read_b128 v[178:181], v220 offset:36864
	ds_read_b128 v[182:185], v220 offset:37888
	ds_read_b128 v[194:197], v220 offset:38912
	ds_read_b128 v[222:225], v220 offset:39936
	global_load_lds_dwordx4 v[230:231], off
	v_lshl_add_u64 v[230:231], s[8:9], 0, v[186:187]
	s_mov_b32 m0, s28
	s_nop 0
	global_load_lds_dwordx4 v[230:231], off
	s_waitcnt vmcnt(8)
	s_waitcnt lgkmcnt(0)
	s_barrier
	s_setprio 1
	s_waitcnt lgkmcnt(0)
	v_mfma_f32_16x16x32_bf16 v[126:129], v[130:133], v[162:165], v[126:129]
	v_mfma_f32_16x16x32_bf16 v[122:125], v[138:141], v[162:165], v[122:125]
	v_mfma_f32_16x16x32_bf16 v[118:121], v[146:149], v[162:165], v[118:121]
	v_mfma_f32_16x16x32_bf16 v[114:117], v[154:157], v[162:165], v[114:117]
	v_mfma_f32_16x16x32_bf16 v[110:113], v[130:133], v[170:173], v[110:113]
	v_mfma_f32_16x16x32_bf16 v[106:109], v[138:141], v[170:173], v[106:109]
	v_mfma_f32_16x16x32_bf16 v[102:105], v[146:149], v[170:173], v[102:105]
	v_mfma_f32_16x16x32_bf16 v[98:101], v[154:157], v[170:173], v[98:101]
	v_mfma_f32_16x16x32_bf16 v[94:97], v[130:133], v[178:181], v[94:97]
	v_mfma_f32_16x16x32_bf16 v[90:93], v[138:141], v[178:181], v[90:93]
	v_mfma_f32_16x16x32_bf16 v[86:89], v[146:149], v[178:181], v[86:89]
	v_mfma_f32_16x16x32_bf16 v[82:85], v[154:157], v[178:181], v[82:85]
	v_mfma_f32_16x16x32_bf16 v[78:81], v[130:133], v[194:197], v[78:81]
	v_mfma_f32_16x16x32_bf16 v[74:77], v[138:141], v[194:197], v[74:77]
	v_mfma_f32_16x16x32_bf16 v[70:73], v[146:149], v[194:197], v[70:73]
	v_mfma_f32_16x16x32_bf16 v[66:69], v[154:157], v[194:197], v[66:69]
	s_setprio 0
	s_setprio 1
	v_mfma_f32_16x16x32_bf16 v[126:129], v[134:137], v[166:169], v[126:129]
	v_mfma_f32_16x16x32_bf16 v[122:125], v[142:145], v[166:169], v[122:125]
	v_mfma_f32_16x16x32_bf16 v[118:121], v[150:153], v[166:169], v[118:121]
	v_mfma_f32_16x16x32_bf16 v[114:117], v[158:161], v[166:169], v[114:117]
	v_mfma_f32_16x16x32_bf16 v[110:113], v[134:137], v[174:177], v[110:113]
	v_mfma_f32_16x16x32_bf16 v[106:109], v[142:145], v[174:177], v[106:109]
	v_mfma_f32_16x16x32_bf16 v[102:105], v[150:153], v[174:177], v[102:105]
	v_mfma_f32_16x16x32_bf16 v[98:101], v[158:161], v[174:177], v[98:101]
	v_mfma_f32_16x16x32_bf16 v[94:97], v[134:137], v[182:185], v[94:97]
	v_mfma_f32_16x16x32_bf16 v[90:93], v[142:145], v[182:185], v[90:93]
	v_mfma_f32_16x16x32_bf16 v[86:89], v[150:153], v[182:185], v[86:89]
	v_mfma_f32_16x16x32_bf16 v[82:85], v[158:161], v[182:185], v[82:85]
	v_mfma_f32_16x16x32_bf16 v[78:81], v[134:137], v[222:225], v[78:81]
	v_mfma_f32_16x16x32_bf16 v[74:77], v[142:145], v[222:225], v[74:77]
	v_mfma_f32_16x16x32_bf16 v[70:73], v[150:153], v[222:225], v[70:73]
	v_mfma_f32_16x16x32_bf16 v[66:69], v[158:161], v[222:225], v[66:69]
	s_setprio 0
	s_barrier
	s_add_i32 s8, s35, s14
	v_lshl_add_u64 v[198:199], v[198:199], 0, s[72:73]
	s_mov_b32 m0, s8
	ds_read_b128 v[162:165], v220 offset:49152
	ds_read_b128 v[166:169], v220 offset:50176
	ds_read_b128 v[170:173], v220 offset:51200
	ds_read_b128 v[174:177], v220 offset:52224
	ds_read_b128 v[178:181], v220 offset:53248
	ds_read_b128 v[182:185], v220 offset:54272
	ds_read_b128 v[194:197], v220 offset:55296
	ds_read_b128 v[222:225], v220 offset:56320
	global_load_lds_dwordx4 v[198:199], off
	s_add_i32 m0, s8, 0x2000
	s_add_u32 s8, s10, 0x80080
	v_lshl_add_u64 v[198:199], v[208:209], 0, s[72:73]
	s_addc_u32 s9, s11, 0
	s_add_i32 s10, s36, s14
	global_load_lds_dwordx4 v[198:199], off
	v_lshl_add_u64 v[198:199], s[8:9], 0, v[188:189]
	s_mov_b32 m0, s10
	s_nop 0
	global_load_lds_dwordx4 v[198:199], off
	v_lshl_add_u64 v[198:199], s[8:9], 0, v[186:187]
	s_add_i32 m0, s10, 0x2000
	s_nop 0
	global_load_lds_dwordx4 v[198:199], off
	v_lshl_add_u64 v[198:199], v[226:227], 0, s[72:73]
	s_mov_b32 m0, s31
	s_nop 0
	global_load_lds_dwordx4 v[198:199], off
	v_lshl_add_u64 v[198:199], v[228:229], 0, s[72:73]
	s_mov_b32 m0, s48
	s_nop 0
	global_load_lds_dwordx4 v[198:199], off
	s_waitcnt vmcnt(8)
	s_waitcnt lgkmcnt(0)
	s_barrier
	s_setprio 1
	s_waitcnt lgkmcnt(0)
	v_mfma_f32_16x16x32_bf16 v[62:65], v[130:133], v[162:165], v[62:65]
	v_mfma_f32_16x16x32_bf16 v[58:61], v[138:141], v[162:165], v[58:61]
	v_mfma_f32_16x16x32_bf16 v[54:57], v[146:149], v[162:165], v[54:57]
	v_mfma_f32_16x16x32_bf16 v[50:53], v[154:157], v[162:165], v[50:53]
	v_mfma_f32_16x16x32_bf16 v[46:49], v[130:133], v[170:173], v[46:49]
	v_mfma_f32_16x16x32_bf16 v[42:45], v[138:141], v[170:173], v[42:45]
	v_mfma_f32_16x16x32_bf16 v[38:41], v[146:149], v[170:173], v[38:41]
	v_mfma_f32_16x16x32_bf16 v[34:37], v[154:157], v[170:173], v[34:37]
	v_mfma_f32_16x16x32_bf16 v[30:33], v[130:133], v[178:181], v[30:33]
	v_mfma_f32_16x16x32_bf16 v[26:29], v[138:141], v[178:181], v[26:29]
	v_mfma_f32_16x16x32_bf16 v[22:25], v[146:149], v[178:181], v[22:25]
	v_mfma_f32_16x16x32_bf16 v[18:21], v[154:157], v[178:181], v[18:21]
	v_mfma_f32_16x16x32_bf16 v[14:17], v[130:133], v[194:197], v[14:17]
	v_mfma_f32_16x16x32_bf16 v[10:13], v[138:141], v[194:197], v[10:13]
	v_mfma_f32_16x16x32_bf16 v[6:9], v[146:149], v[194:197], v[6:9]
	v_mfma_f32_16x16x32_bf16 v[2:5], v[154:157], v[194:197], v[2:5]
	s_setprio 0
	s_setprio 1
	v_mfma_f32_16x16x32_bf16 v[62:65], v[134:137], v[166:169], v[62:65]
	v_mfma_f32_16x16x32_bf16 v[58:61], v[142:145], v[166:169], v[58:61]
	v_mfma_f32_16x16x32_bf16 v[54:57], v[150:153], v[166:169], v[54:57]
	v_mfma_f32_16x16x32_bf16 v[50:53], v[158:161], v[166:169], v[50:53]
	v_mfma_f32_16x16x32_bf16 v[46:49], v[134:137], v[174:177], v[46:49]
	v_mfma_f32_16x16x32_bf16 v[42:45], v[142:145], v[174:177], v[42:45]
	v_mfma_f32_16x16x32_bf16 v[38:41], v[150:153], v[174:177], v[38:41]
	v_mfma_f32_16x16x32_bf16 v[34:37], v[158:161], v[174:177], v[34:37]
	v_mfma_f32_16x16x32_bf16 v[30:33], v[134:137], v[182:185], v[30:33]
	v_mfma_f32_16x16x32_bf16 v[26:29], v[142:145], v[182:185], v[26:29]
	v_mfma_f32_16x16x32_bf16 v[22:25], v[150:153], v[182:185], v[22:25]
	v_mfma_f32_16x16x32_bf16 v[18:21], v[158:161], v[182:185], v[18:21]
	v_mfma_f32_16x16x32_bf16 v[14:17], v[134:137], v[222:225], v[14:17]
	v_mfma_f32_16x16x32_bf16 v[10:13], v[142:145], v[222:225], v[10:13]
	v_mfma_f32_16x16x32_bf16 v[6:9], v[150:153], v[222:225], v[6:9]
	v_mfma_f32_16x16x32_bf16 v[2:5], v[158:161], v[222:225], v[2:5]
	s_setprio 0
	s_barrier
	s_add_i32 s34, s34, 2
	s_add_u32 s23, s23, 0x100
	s_addc_u32 s33, s33, 0
	s_cmp_gt_u32 s34, 29
	s_mov_b64 s[8:9], s[0:1]
	s_cbranch_scc0 .LBB0_559
	s_and_b64 vcc, exec, s[54:55]
	s_cbranch_vccz .LBB0_562
	s_barrier

.LBB0_681:
	v_add_u32_e32 v1, 0x10000, v241
	ds_read_b128 v[148:151], v1
	ds_read_b128 v[152:155], v1 offset:1024
	ds_read_b128 v[156:159], v1 offset:2048
	ds_read_b128 v[160:163], v1 offset:3072
	v_add_u32_e32 v1, 0x14000, v241
	ds_read_b128 v[132:135], v1
	ds_read_b128 v[136:139], v1 offset:1024
	ds_read_b128 v[140:143], v1 offset:2048
	ds_read_b128 v[144:147], v1 offset:3072
	v_lshl_add_u64 v[2:3], v[222:223], 0, s[0:1]
	s_add_i32 m0, s31, 0xc000
	s_waitcnt lgkmcnt(0)
	ds_read_b128 v[176:179], v242
	ds_read_b128 v[192:195], v242 offset:1024
	ds_read_b128 v[172:175], v242 offset:2048
	ds_read_b128 v[188:191], v242 offset:3072
	ds_read_b128 v[168:171], v242 offset:4096
	ds_read_b128 v[184:187], v242 offset:5120
	ds_read_b128 v[164:167], v242 offset:6144
	ds_read_b128 v[180:183], v242 offset:7168
	global_load_lds_dwordx4 v[2:3], off
	v_lshl_add_u64 v[2:3], v[220:221], 0, s[0:1]
	s_add_i32 m0, s31, 0xe000
	s_nop 0
	global_load_lds_dwordx4 v[2:3], off
	s_waitcnt vmcnt(8)
	s_waitcnt lgkmcnt(0)
	s_barrier
	s_setprio 1
	s_waitcnt lgkmcnt(0)
	v_mfma_f32_16x16x32_bf16 v[128:131], v[148:151], v[176:179], v[128:131]
	v_mfma_f32_16x16x32_bf16 v[124:127], v[156:159], v[176:179], v[124:127]
	v_mfma_f32_16x16x32_bf16 v[120:123], v[132:135], v[176:179], v[120:123]
	v_mfma_f32_16x16x32_bf16 v[116:119], v[140:143], v[176:179], v[116:119]
	v_mfma_f32_16x16x32_bf16 v[112:115], v[148:151], v[172:175], v[112:115]
	v_mfma_f32_16x16x32_bf16 v[108:111], v[156:159], v[172:175], v[108:111]
	v_mfma_f32_16x16x32_bf16 v[104:107], v[132:135], v[172:175], v[104:107]
	v_mfma_f32_16x16x32_bf16 v[100:103], v[140:143], v[172:175], v[100:103]
	v_mfma_f32_16x16x32_bf16 v[96:99], v[148:151], v[168:171], v[96:99]
	v_mfma_f32_16x16x32_bf16 v[92:95], v[156:159], v[168:171], v[92:95]
	v_mfma_f32_16x16x32_bf16 v[88:91], v[132:135], v[168:171], v[88:91]
	v_mfma_f32_16x16x32_bf16 v[84:87], v[140:143], v[168:171], v[84:87]
	v_mfma_f32_16x16x32_bf16 v[80:83], v[148:151], v[164:167], v[80:83]
	v_mfma_f32_16x16x32_bf16 v[76:79], v[156:159], v[164:167], v[76:79]
	v_mfma_f32_16x16x32_bf16 v[72:75], v[132:135], v[164:167], v[72:75]
	v_mfma_f32_16x16x32_bf16 v[68:71], v[140:143], v[164:167], v[68:71]
	s_setprio 0
	s_setprio 1
	v_mfma_f32_16x16x32_bf16 v[128:131], v[152:155], v[192:195], v[128:131]
	v_mfma_f32_16x16x32_bf16 v[124:127], v[160:163], v[192:195], v[124:127]
	v_mfma_f32_16x16x32_bf16 v[120:123], v[136:139], v[192:195], v[120:123]
	v_mfma_f32_16x16x32_bf16 v[116:119], v[144:147], v[192:195], v[116:119]
	v_mfma_f32_16x16x32_bf16 v[112:115], v[152:155], v[188:191], v[112:115]
	v_mfma_f32_16x16x32_bf16 v[108:111], v[160:163], v[188:191], v[108:111]
	v_mfma_f32_16x16x32_bf16 v[104:107], v[136:139], v[188:191], v[104:107]
	v_mfma_f32_16x16x32_bf16 v[100:103], v[144:147], v[188:191], v[100:103]
	v_mfma_f32_16x16x32_bf16 v[96:99], v[152:155], v[184:187], v[96:99]
	v_mfma_f32_16x16x32_bf16 v[92:95], v[160:163], v[184:187], v[92:95]
	v_mfma_f32_16x16x32_bf16 v[88:91], v[136:139], v[184:187], v[88:91]
	v_mfma_f32_16x16x32_bf16 v[84:87], v[144:147], v[184:187], v[84:87]
	v_mfma_f32_16x16x32_bf16 v[80:83], v[152:155], v[180:183], v[80:83]
	v_mfma_f32_16x16x32_bf16 v[76:79], v[160:163], v[180:183], v[76:79]
	v_mfma_f32_16x16x32_bf16 v[72:75], v[136:139], v[180:183], v[72:75]
	v_mfma_f32_16x16x32_bf16 v[68:71], v[144:147], v[180:183], v[68:71]
	s_setprio 0
	s_barrier
	v_cndmask_b32_e64 v1, 0, 1, s[14:15]
	v_cmp_ne_u32_e64 s[40:41], 1, v1
	s_andn2_b64 vcc, exec, s[14:15]
	s_cbranch_vccnz .LBB0_683
	ds_read_b128 v[176:179], v242 offset:16384
	ds_read_b128 v[192:195], v242 offset:17408
	ds_read_b128 v[172:175], v242 offset:18432
	ds_read_b128 v[188:191], v242 offset:19456
	ds_read_b128 v[168:171], v242 offset:20480
	ds_read_b128 v[184:187], v242 offset:21504
	ds_read_b128 v[164:167], v242 offset:22528
	ds_read_b128 v[180:183], v242 offset:23552
.LBB0_683:
	s_add_u32 s16, s10, s0
	s_addc_u32 s17, s11, s1
	s_add_u32 s20, s16, 0x100
	s_addc_u32 s21, s17, 0
	s_add_u32 s70, s55, s0
	s_addc_u32 s71, s68, s1
	s_cmpk_eq_i32 s0, 0xf00
	s_cselect_b64 s[26:27], -1, 0
	s_and_b64 s[16:17], s[26:27], exec
	s_cselect_b32 s17, s35, s71
	s_cselect_b32 s16, s47, s70
	s_mov_b32 m0, s36
	s_cselect_b32 s21, s33, s21
	s_cselect_b32 s20, s34, s20
	v_lshl_add_u64 v[2:3], s[16:17], 0, v[212:213]
	s_add_u32 s70, s16, 0x80000
	global_load_lds_dwordx4 v[2:3], off
	v_lshl_add_u64 v[224:225], s[16:17], 0, v[208:209]
	s_mov_b32 m0, s37
	s_addc_u32 s71, s17, 0
	global_load_lds_dwordx4 v[224:225], off
	v_lshl_add_u64 v[196:197], s[70:71], 0, v[212:213]
	s_mov_b32 m0, s48
	v_lshl_add_u64 v[226:227], s[20:21], 0, v[214:215]
	global_load_lds_dwordx4 v[196:197], off
	v_lshl_add_u64 v[196:197], s[70:71], 0, v[208:209]
	s_mov_b32 m0, s49
	v_lshl_add_u64 v[228:229], s[20:21], 0, v[210:211]
	global_load_lds_dwordx4 v[196:197], off
	s_mov_b32 m0, s31
	s_and_b64 vcc, exec, s[40:41]
	global_load_lds_dwordx4 v[226:227], off
	s_mov_b32 m0, s50
	s_nop 0
	global_load_lds_dwordx4 v[228:229], off
	s_waitcnt vmcnt(8)
	s_waitcnt lgkmcnt(0)
	s_cbranch_vccnz .Lskp_g1
	s_barrier
	s_setprio 1
	s_waitcnt lgkmcnt(0)
	v_mfma_f32_16x16x32_bf16 v[64:67], v[148:151], v[176:179], v[64:67]
	v_mfma_f32_16x16x32_bf16 v[60:63], v[156:159], v[176:179], v[60:63]
	v_mfma_f32_16x16x32_bf16 v[56:59], v[132:135], v[176:179], v[56:59]
	v_mfma_f32_16x16x32_bf16 v[52:55], v[140:143], v[176:179], v[52:55]
	v_mfma_f32_16x16x32_bf16 v[48:51], v[148:151], v[172:175], v[48:51]
	v_mfma_f32_16x16x32_bf16 v[44:47], v[156:159], v[172:175], v[44:47]
	v_mfma_f32_16x16x32_bf16 v[40:43], v[132:135], v[172:175], v[40:43]
	v_mfma_f32_16x16x32_bf16 v[36:39], v[140:143], v[172:175], v[36:39]
	v_mfma_f32_16x16x32_bf16 v[32:35], v[148:151], v[168:171], v[32:35]
	v_mfma_f32_16x16x32_bf16 v[28:31], v[156:159], v[168:171], v[28:31]
	v_mfma_f32_16x16x32_bf16 v[24:27], v[132:135], v[168:171], v[24:27]
	v_mfma_f32_16x16x32_bf16 v[20:23], v[140:143], v[168:171], v[20:23]
	v_mfma_f32_16x16x32_bf16 v[16:19], v[148:151], v[164:167], v[16:19]
	v_mfma_f32_16x16x32_bf16 v[12:15], v[156:159], v[164:167], v[12:15]
	v_mfma_f32_16x16x32_bf16 v[8:11], v[132:135], v[164:167], v[8:11]
	v_mfma_f32_16x16x32_bf16 v[4:7], v[140:143], v[164:167], v[4:7]
	s_setprio 0
	s_setprio 1
	v_mfma_f32_16x16x32_bf16 v[64:67], v[152:155], v[192:195], v[64:67]
	v_mfma_f32_16x16x32_bf16 v[60:63], v[160:163], v[192:195], v[60:63]
	v_mfma_f32_16x16x32_bf16 v[56:59], v[136:139], v[192:195], v[56:59]
	v_mfma_f32_16x16x32_bf16 v[52:55], v[144:147], v[192:195], v[52:55]
	v_mfma_f32_16x16x32_bf16 v[48:51], v[152:155], v[188:191], v[48:51]
	v_mfma_f32_16x16x32_bf16 v[44:47], v[160:163], v[188:191], v[44:47]
	v_mfma_f32_16x16x32_bf16 v[40:43], v[136:139], v[188:191], v[40:43]
	v_mfma_f32_16x16x32_bf16 v[36:39], v[144:147], v[188:191], v[36:39]
	v_mfma_f32_16x16x32_bf16 v[32:35], v[152:155], v[184:187], v[32:35]
	v_mfma_f32_16x16x32_bf16 v[28:31], v[160:163], v[184:187], v[28:31]
	v_mfma_f32_16x16x32_bf16 v[24:27], v[136:139], v[184:187], v[24:27]
	v_mfma_f32_16x16x32_bf16 v[20:23], v[144:147], v[184:187], v[20:23]
	v_mfma_f32_16x16x32_bf16 v[16:19], v[152:155], v[180:183], v[16:19]
	v_mfma_f32_16x16x32_bf16 v[12:15], v[160:163], v[180:183], v[12:15]
	v_mfma_f32_16x16x32_bf16 v[8:11], v[136:139], v[180:183], v[8:11]
	v_mfma_f32_16x16x32_bf16 v[4:7], v[144:147], v[180:183], v[4:7]
	s_setprio 0
.LBB0_685:
	s_barrier
	v_add_u32_e32 v1, 0x18000, v241
	ds_read_b128 v[148:151], v1
	ds_read_b128 v[152:155], v1 offset:1024
	ds_read_b128 v[156:159], v1 offset:2048
	ds_read_b128 v[160:163], v1 offset:3072
	v_add_u32_e32 v1, 0x1c000, v241
	ds_read_b128 v[132:135], v1
	ds_read_b128 v[136:139], v1 offset:1024
	ds_read_b128 v[140:143], v1 offset:2048
	ds_read_b128 v[144:147], v1 offset:3072
	s_and_b64 s[26:27], s[38:39], s[26:27]
	s_and_b64 s[26:27], s[26:27], exec
	s_cselect_b32 s27, s52, s12
	s_cselect_b32 s26, 0, s13
	s_add_u32 s20, s20, s27
	s_addc_u32 s21, s21, s26
	s_mov_b32 m0, s51
	v_lshl_add_u64 v[196:197], s[20:21], 0, v[214:215]
	s_waitcnt lgkmcnt(0)
	ds_read_b128 v[176:179], v242 offset:32768
	ds_read_b128 v[192:195], v242 offset:33792
	ds_read_b128 v[172:175], v242 offset:34816
	ds_read_b128 v[188:191], v242 offset:35840
	ds_read_b128 v[168:171], v242 offset:36864
	ds_read_b128 v[184:187], v242 offset:37888
	ds_read_b128 v[164:167], v242 offset:38912
	ds_read_b128 v[180:183], v242 offset:39936
	global_load_lds_dwordx4 v[196:197], off
	v_lshl_add_u64 v[196:197], s[20:21], 0, v[210:211]
	s_mov_b32 m0, s60
	s_nop 0
	global_load_lds_dwordx4 v[196:197], off
	s_waitcnt vmcnt(8)
	s_waitcnt lgkmcnt(0)
	s_barrier
	s_setprio 1
	s_waitcnt lgkmcnt(0)
	v_mfma_f32_16x16x32_bf16 v[128:131], v[148:151], v[176:179], v[128:131]
	v_mfma_f32_16x16x32_bf16 v[124:127], v[156:159], v[176:179], v[124:127]
	v_mfma_f32_16x16x32_bf16 v[120:123], v[132:135], v[176:179], v[120:123]
	v_mfma_f32_16x16x32_bf16 v[116:119], v[140:143], v[176:179], v[116:119]
	v_mfma_f32_16x16x32_bf16 v[112:115], v[148:151], v[172:175], v[112:115]
	v_mfma_f32_16x16x32_bf16 v[108:111], v[156:159], v[172:175], v[108:111]
	v_mfma_f32_16x16x32_bf16 v[104:107], v[132:135], v[172:175], v[104:107]
	v_mfma_f32_16x16x32_bf16 v[100:103], v[140:143], v[172:175], v[100:103]
	v_mfma_f32_16x16x32_bf16 v[96:99], v[148:151], v[168:171], v[96:99]
	v_mfma_f32_16x16x32_bf16 v[92:95], v[156:159], v[168:171], v[92:95]
	v_mfma_f32_16x16x32_bf16 v[88:91], v[132:135], v[168:171], v[88:91]
	v_mfma_f32_16x16x32_bf16 v[84:87], v[140:143], v[168:171], v[84:87]
	v_mfma_f32_16x16x32_bf16 v[80:83], v[148:151], v[164:167], v[80:83]
	v_mfma_f32_16x16x32_bf16 v[76:79], v[156:159], v[164:167], v[76:79]
	v_mfma_f32_16x16x32_bf16 v[72:75], v[132:135], v[164:167], v[72:75]
	v_mfma_f32_16x16x32_bf16 v[68:71], v[140:143], v[164:167], v[68:71]
	s_setprio 0
	s_setprio 1
	v_mfma_f32_16x16x32_bf16 v[128:131], v[152:155], v[192:195], v[128:131]
	v_mfma_f32_16x16x32_bf16 v[124:127], v[160:163], v[192:195], v[124:127]
	v_mfma_f32_16x16x32_bf16 v[120:123], v[136:139], v[192:195], v[120:123]
	v_mfma_f32_16x16x32_bf16 v[116:119], v[144:147], v[192:195], v[116:119]
	v_mfma_f32_16x16x32_bf16 v[112:115], v[152:155], v[188:191], v[112:115]
	v_mfma_f32_16x16x32_bf16 v[108:111], v[160:163], v[188:191], v[108:111]
	v_mfma_f32_16x16x32_bf16 v[104:107], v[136:139], v[188:191], v[104:107]
	v_mfma_f32_16x16x32_bf16 v[100:103], v[144:147], v[188:191], v[100:103]
	v_mfma_f32_16x16x32_bf16 v[96:99], v[152:155], v[184:187], v[96:99]
	v_mfma_f32_16x16x32_bf16 v[92:95], v[160:163], v[184:187], v[92:95]
	v_mfma_f32_16x16x32_bf16 v[88:91], v[136:139], v[184:187], v[88:91]
	v_mfma_f32_16x16x32_bf16 v[84:87], v[144:147], v[184:187], v[84:87]
	v_mfma_f32_16x16x32_bf16 v[80:83], v[152:155], v[180:183], v[80:83]
	v_mfma_f32_16x16x32_bf16 v[76:79], v[160:163], v[180:183], v[76:79]
	v_mfma_f32_16x16x32_bf16 v[72:75], v[136:139], v[180:183], v[72:75]
	v_mfma_f32_16x16x32_bf16 v[68:71], v[144:147], v[180:183], v[68:71]
	s_setprio 0
	s_barrier
	s_and_b64 vcc, exec, s[40:41]
	s_cbranch_vccnz .LBB0_687
	ds_read_b128 v[176:179], v242 offset:49152
	ds_read_b128 v[192:195], v242 offset:50176
	ds_read_b128 v[172:175], v242 offset:51200
	ds_read_b128 v[188:191], v242 offset:52224
	ds_read_b128 v[168:171], v242 offset:53248
	ds_read_b128 v[184:187], v242 offset:54272
	ds_read_b128 v[164:167], v242 offset:55296
	ds_read_b128 v[180:183], v242 offset:56320
.LBB0_687:
	s_mov_b32 m0, s61
	v_lshl_add_u64 v[2:3], v[2:3], 0, s[72:73]
	s_add_u32 s16, s16, 0x80080
	global_load_lds_dwordx4 v[2:3], off
	v_lshl_add_u64 v[2:3], v[224:225], 0, s[72:73]
	s_mov_b32 m0, s62
	s_addc_u32 s17, s17, 0
	global_load_lds_dwordx4 v[2:3], off
	v_lshl_add_u64 v[2:3], s[16:17], 0, v[212:213]
	s_mov_b32 m0, s65
	s_and_b64 vcc, exec, s[40:41]
	global_load_lds_dwordx4 v[2:3], off
	v_lshl_add_u64 v[2:3], s[16:17], 0, v[208:209]
	s_mov_b32 m0, s66
	s_nop 0
	global_load_lds_dwordx4 v[2:3], off
	v_lshl_add_u64 v[2:3], v[226:227], 0, s[72:73]
	s_mov_b32 m0, s63
	s_nop 0
	global_load_lds_dwordx4 v[2:3], off
	v_lshl_add_u64 v[2:3], v[228:229], 0, s[72:73]
	s_mov_b32 m0, s64
	s_nop 0
	global_load_lds_dwordx4 v[2:3], off
	s_waitcnt vmcnt(8)
	s_waitcnt lgkmcnt(0)
	s_cbranch_vccnz .Lskp_g2
	s_barrier
	s_setprio 1
	s_waitcnt lgkmcnt(0)
	v_mfma_f32_16x16x32_bf16 v[64:67], v[148:151], v[176:179], v[64:67]
	v_mfma_f32_16x16x32_bf16 v[60:63], v[156:159], v[176:179], v[60:63]
	v_mfma_f32_16x16x32_bf16 v[56:59], v[132:135], v[176:179], v[56:59]
	v_mfma_f32_16x16x32_bf16 v[52:55], v[140:143], v[176:179], v[52:55]
	v_mfma_f32_16x16x32_bf16 v[48:51], v[148:151], v[172:175], v[48:51]
	v_mfma_f32_16x16x32_bf16 v[44:47], v[156:159], v[172:175], v[44:47]
	v_mfma_f32_16x16x32_bf16 v[40:43], v[132:135], v[172:175], v[40:43]
	v_mfma_f32_16x16x32_bf16 v[36:39], v[140:143], v[172:175], v[36:39]
	v_mfma_f32_16x16x32_bf16 v[32:35], v[148:151], v[168:171], v[32:35]
	v_mfma_f32_16x16x32_bf16 v[28:31], v[156:159], v[168:171], v[28:31]
	v_mfma_f32_16x16x32_bf16 v[24:27], v[132:135], v[168:171], v[24:27]
	v_mfma_f32_16x16x32_bf16 v[20:23], v[140:143], v[168:171], v[20:23]
	v_mfma_f32_16x16x32_bf16 v[16:19], v[148:151], v[164:167], v[16:19]
	v_mfma_f32_16x16x32_bf16 v[12:15], v[156:159], v[164:167], v[12:15]
	v_mfma_f32_16x16x32_bf16 v[8:11], v[132:135], v[164:167], v[8:11]
	v_mfma_f32_16x16x32_bf16 v[2:5], v[140:143], v[164:167], v[4:7]
	s_setprio 0
	s_setprio 1
	v_mfma_f32_16x16x32_bf16 v[64:67], v[152:155], v[192:195], v[64:67]
	v_mfma_f32_16x16x32_bf16 v[60:63], v[160:163], v[192:195], v[60:63]
	v_mfma_f32_16x16x32_bf16 v[56:59], v[136:139], v[192:195], v[56:59]
	v_mfma_f32_16x16x32_bf16 v[52:55], v[144:147], v[192:195], v[52:55]
	v_mfma_f32_16x16x32_bf16 v[48:51], v[152:155], v[188:191], v[48:51]
	v_mfma_f32_16x16x32_bf16 v[44:47], v[160:163], v[188:191], v[44:47]
	v_mfma_f32_16x16x32_bf16 v[40:43], v[136:139], v[188:191], v[40:43]
	v_mfma_f32_16x16x32_bf16 v[36:39], v[144:147], v[188:191], v[36:39]
	v_mfma_f32_16x16x32_bf16 v[32:35], v[152:155], v[184:187], v[32:35]
	v_mfma_f32_16x16x32_bf16 v[28:31], v[160:163], v[184:187], v[28:31]
	v_mfma_f32_16x16x32_bf16 v[24:27], v[136:139], v[184:187], v[24:27]
	v_mfma_f32_16x16x32_bf16 v[20:23], v[144:147], v[184:187], v[20:23]
	v_mfma_f32_16x16x32_bf16 v[16:19], v[152:155], v[180:183], v[16:19]
	v_mfma_f32_16x16x32_bf16 v[12:15], v[160:163], v[180:183], v[12:15]
	v_mfma_f32_16x16x32_bf16 v[8:11], v[136:139], v[180:183], v[8:11]
	v_mfma_f32_16x16x32_bf16 v[4:7], v[144:147], v[180:183], v[2:5]
	s_setprio 0

.LBB0_765:
	s_add_u32 s0, s14, 0x100
	s_addc_u32 s1, s15, 0
	s_add_i32 s33, 0, 0x10000
	s_cmpk_eq_i32 s22, 0x54
	s_cselect_b32 s21, s11, s1
	s_cselect_b32 s20, s10, s0
	s_cselect_b32 s17, s13, s18
	s_cselect_b32 s16, s12, s3
	s_add_i32 s34, 0, 0x14000
	v_add_u32_e32 v118, s33, v226
	v_add_u32_e32 v158, s34, v226
	ds_read_b128 v[82:85], v118
	ds_read_b128 v[94:97], v118 offset:1024
	ds_read_b128 v[106:109], v118 offset:2048
	ds_read_b128 v[118:121], v118 offset:3072
	ds_read_b128 v[130:133], v158
	ds_read_b128 v[142:145], v158 offset:1024
	ds_read_b128 v[150:153], v158 offset:2048
	ds_read_b128 v[158:161], v158 offset:3072
	v_lshl_add_u64 v[198:199], s[14:15], 0, v[190:191]
	s_add_i32 m0, s30, 0xc000
	ds_read_b128 v[162:165], v231
	ds_read_b128 v[166:169], v231 offset:1024
	ds_read_b128 v[170:173], v231 offset:2048
	ds_read_b128 v[174:177], v231 offset:3072
	ds_read_b128 v[178:181], v231 offset:4096
	ds_read_b128 v[182:185], v231 offset:5120
	ds_read_b128 v[194:197], v231 offset:6144
	ds_read_b128 v[208:211], v231 offset:7168
	global_load_lds_dwordx4 v[198:199], off
	v_lshl_add_u64 v[198:199], s[14:15], 0, v[192:193]
	s_add_i32 m0, s30, 0xe000
	s_nop 0
	global_load_lds_dwordx4 v[198:199], off
	s_waitcnt vmcnt(8)
	s_waitcnt lgkmcnt(0)
	s_barrier
	s_setprio 1
	s_waitcnt lgkmcnt(0)
	v_mfma_f32_16x16x32_bf16 v[154:157], v[82:85], v[162:165], v[154:157]
	v_mfma_f32_16x16x32_bf16 v[146:149], v[106:109], v[162:165], v[146:149]
	v_mfma_f32_16x16x32_bf16 v[138:141], v[130:133], v[162:165], v[138:141]
	v_mfma_f32_16x16x32_bf16 v[134:137], v[150:153], v[162:165], v[134:137]
	v_mfma_f32_16x16x32_bf16 v[126:129], v[82:85], v[170:173], v[126:129]
	v_mfma_f32_16x16x32_bf16 v[122:125], v[106:109], v[170:173], v[122:125]
	v_mfma_f32_16x16x32_bf16 v[114:117], v[130:133], v[170:173], v[114:117]
	v_mfma_f32_16x16x32_bf16 v[110:113], v[150:153], v[170:173], v[110:113]
	v_mfma_f32_16x16x32_bf16 v[102:105], v[82:85], v[178:181], v[102:105]
	v_mfma_f32_16x16x32_bf16 v[98:101], v[106:109], v[178:181], v[98:101]
	v_mfma_f32_16x16x32_bf16 v[90:93], v[130:133], v[178:181], v[90:93]
	v_mfma_f32_16x16x32_bf16 v[86:89], v[150:153], v[178:181], v[86:89]
	v_mfma_f32_16x16x32_bf16 v[78:81], v[82:85], v[194:197], v[78:81]
	v_mfma_f32_16x16x32_bf16 v[74:77], v[106:109], v[194:197], v[74:77]
	v_mfma_f32_16x16x32_bf16 v[70:73], v[130:133], v[194:197], v[70:73]
	v_mfma_f32_16x16x32_bf16 v[66:69], v[150:153], v[194:197], v[66:69]
	s_setprio 0
	s_setprio 1
	v_mfma_f32_16x16x32_bf16 v[154:157], v[94:97], v[166:169], v[154:157]
	v_mfma_f32_16x16x32_bf16 v[146:149], v[118:121], v[166:169], v[146:149]
	v_mfma_f32_16x16x32_bf16 v[138:141], v[142:145], v[166:169], v[138:141]
	v_mfma_f32_16x16x32_bf16 v[134:137], v[158:161], v[166:169], v[134:137]
	v_mfma_f32_16x16x32_bf16 v[126:129], v[94:97], v[174:177], v[126:129]
	v_mfma_f32_16x16x32_bf16 v[122:125], v[118:121], v[174:177], v[122:125]
	v_mfma_f32_16x16x32_bf16 v[114:117], v[142:145], v[174:177], v[114:117]
	v_mfma_f32_16x16x32_bf16 v[110:113], v[158:161], v[174:177], v[110:113]
	v_mfma_f32_16x16x32_bf16 v[102:105], v[94:97], v[182:185], v[102:105]
	v_mfma_f32_16x16x32_bf16 v[98:101], v[118:121], v[182:185], v[98:101]
	v_mfma_f32_16x16x32_bf16 v[90:93], v[142:145], v[182:185], v[90:93]
	v_mfma_f32_16x16x32_bf16 v[86:89], v[158:161], v[182:185], v[86:89]
	v_mfma_f32_16x16x32_bf16 v[78:81], v[94:97], v[208:211], v[78:81]
	v_mfma_f32_16x16x32_bf16 v[74:77], v[118:121], v[208:211], v[74:77]
	v_mfma_f32_16x16x32_bf16 v[70:73], v[142:145], v[208:211], v[70:73]
	v_mfma_f32_16x16x32_bf16 v[66:69], v[158:161], v[208:211], v[66:69]
	s_setprio 0
	s_barrier
	s_add_i32 s14, s33, s29
	v_lshl_add_u64 v[198:199], s[16:17], 0, v[188:189]
	s_mov_b32 m0, s14
	ds_read_b128 v[162:165], v231 offset:16384
	ds_read_b128 v[166:169], v231 offset:17408
	ds_read_b128 v[170:173], v231 offset:18432
	ds_read_b128 v[174:177], v231 offset:19456
	ds_read_b128 v[178:181], v231 offset:20480
	ds_read_b128 v[182:185], v231 offset:21504
	ds_read_b128 v[194:197], v231 offset:22528
	ds_read_b128 v[208:211], v231 offset:23552
	global_load_lds_dwordx4 v[198:199], off
	s_add_i32 m0, s14, 0x2000
	s_add_u32 s14, s16, 0x160000
	v_lshl_add_u64 v[212:213], s[16:17], 0, v[186:187]
	s_addc_u32 s15, s17, 0
	s_add_i32 s33, s34, s29
	global_load_lds_dwordx4 v[212:213], off
	v_lshl_add_u64 v[214:215], s[14:15], 0, v[188:189]
	s_mov_b32 m0, s33
	v_lshl_add_u64 v[216:217], s[20:21], 0, v[186:187]
	global_load_lds_dwordx4 v[214:215], off
	v_lshl_add_u64 v[214:215], s[14:15], 0, v[186:187]
	s_add_i32 m0, s33, 0x2000
	s_nop 0
	global_load_lds_dwordx4 v[214:215], off
	v_lshl_add_u64 v[214:215], s[20:21], 0, v[188:189]
	s_mov_b32 m0, s30
	s_nop 0
	global_load_lds_dwordx4 v[214:215], off
	s_mov_b32 m0, s31
	s_nop 0
	global_load_lds_dwordx4 v[216:217], off
	s_waitcnt vmcnt(8)
	s_waitcnt lgkmcnt(0)
	s_barrier
	s_setprio 1
	s_waitcnt lgkmcnt(0)
	v_mfma_f32_16x16x32_bf16 v[62:65], v[82:85], v[162:165], v[62:65]
	v_mfma_f32_16x16x32_bf16 v[58:61], v[106:109], v[162:165], v[58:61]
	v_mfma_f32_16x16x32_bf16 v[54:57], v[130:133], v[162:165], v[54:57]
	v_mfma_f32_16x16x32_bf16 v[50:53], v[150:153], v[162:165], v[50:53]
	v_mfma_f32_16x16x32_bf16 v[46:49], v[82:85], v[170:173], v[46:49]
	v_mfma_f32_16x16x32_bf16 v[42:45], v[106:109], v[170:173], v[42:45]
	v_mfma_f32_16x16x32_bf16 v[38:41], v[130:133], v[170:173], v[38:41]
	v_mfma_f32_16x16x32_bf16 v[34:37], v[150:153], v[170:173], v[34:37]
	v_mfma_f32_16x16x32_bf16 v[30:33], v[82:85], v[178:181], v[30:33]
	v_mfma_f32_16x16x32_bf16 v[26:29], v[106:109], v[178:181], v[26:29]
	v_mfma_f32_16x16x32_bf16 v[22:25], v[130:133], v[178:181], v[22:25]
	v_mfma_f32_16x16x32_bf16 v[18:21], v[150:153], v[178:181], v[18:21]
	v_mfma_f32_16x16x32_bf16 v[14:17], v[82:85], v[194:197], v[14:17]
	v_mfma_f32_16x16x32_bf16 v[10:13], v[106:109], v[194:197], v[10:13]
	v_mfma_f32_16x16x32_bf16 v[6:9], v[130:133], v[194:197], v[6:9]
	v_mfma_f32_16x16x32_bf16 v[2:5], v[150:153], v[194:197], v[2:5]
	s_setprio 0
	s_setprio 1
	v_mfma_f32_16x16x32_bf16 v[62:65], v[94:97], v[166:169], v[62:65]
	v_mfma_f32_16x16x32_bf16 v[58:61], v[118:121], v[166:169], v[58:61]
	v_mfma_f32_16x16x32_bf16 v[54:57], v[142:145], v[166:169], v[54:57]
	v_mfma_f32_16x16x32_bf16 v[50:53], v[158:161], v[166:169], v[50:53]
	v_mfma_f32_16x16x32_bf16 v[46:49], v[94:97], v[174:177], v[46:49]
	v_mfma_f32_16x16x32_bf16 v[42:45], v[118:121], v[174:177], v[42:45]
	v_mfma_f32_16x16x32_bf16 v[38:41], v[142:145], v[174:177], v[38:41]
	v_mfma_f32_16x16x32_bf16 v[34:37], v[158:161], v[174:177], v[34:37]
	v_mfma_f32_16x16x32_bf16 v[30:33], v[94:97], v[182:185], v[30:33]
	v_mfma_f32_16x16x32_bf16 v[26:29], v[118:121], v[182:185], v[26:29]
	v_mfma_f32_16x16x32_bf16 v[22:25], v[142:145], v[182:185], v[22:25]
	v_mfma_f32_16x16x32_bf16 v[18:21], v[158:161], v[182:185], v[18:21]
	v_mfma_f32_16x16x32_bf16 v[14:17], v[94:97], v[208:211], v[14:17]
	v_mfma_f32_16x16x32_bf16 v[10:13], v[118:121], v[208:211], v[10:13]
	v_mfma_f32_16x16x32_bf16 v[6:9], v[142:145], v[208:211], v[6:9]
	v_mfma_f32_16x16x32_bf16 v[2:5], v[158:161], v[208:211], v[2:5]
	s_setprio 0
	s_barrier
	s_add_i32 s33, 0, 0x18000
	s_add_i32 s34, 0, 0x1c000
	v_add_u32_e32 v118, s33, v226
	v_add_u32_e32 v158, s34, v226
	ds_read_b128 v[82:85], v118
	ds_read_b128 v[94:97], v118 offset:1024
	ds_read_b128 v[106:109], v118 offset:2048
	ds_read_b128 v[118:121], v118 offset:3072
	ds_read_b128 v[130:133], v158
	ds_read_b128 v[142:145], v158 offset:1024
	ds_read_b128 v[150:153], v158 offset:2048
	ds_read_b128 v[158:161], v158 offset:3072
	s_add_u32 s14, s20, 0x160000
	s_addc_u32 s15, s21, 0
	s_mov_b32 m0, s36
	v_lshl_add_u64 v[218:219], s[14:15], 0, v[188:189]
	ds_read_b128 v[162:165], v231 offset:32768
	ds_read_b128 v[166:169], v231 offset:33792
	ds_read_b128 v[170:173], v231 offset:34816
	ds_read_b128 v[174:177], v231 offset:35840
	ds_read_b128 v[178:181], v231 offset:36864
	ds_read_b128 v[182:185], v231 offset:37888
	ds_read_b128 v[194:197], v231 offset:38912
	ds_read_b128 v[208:211], v231 offset:39936
	global_load_lds_dwordx4 v[218:219], off
	v_lshl_add_u64 v[218:219], s[14:15], 0, v[186:187]
	s_mov_b32 m0, s37
	s_nop 0
	global_load_lds_dwordx4 v[218:219], off
	s_waitcnt vmcnt(8)
	s_waitcnt lgkmcnt(0)
	s_barrier
	s_setprio 1
	s_waitcnt lgkmcnt(0)
	v_mfma_f32_16x16x32_bf16 v[154:157], v[82:85], v[162:165], v[154:157]
	v_mfma_f32_16x16x32_bf16 v[146:149], v[106:109], v[162:165], v[146:149]
	v_mfma_f32_16x16x32_bf16 v[138:141], v[130:133], v[162:165], v[138:141]
	v_mfma_f32_16x16x32_bf16 v[134:137], v[150:153], v[162:165], v[134:137]
	v_mfma_f32_16x16x32_bf16 v[126:129], v[82:85], v[170:173], v[126:129]
	v_mfma_f32_16x16x32_bf16 v[122:125], v[106:109], v[170:173], v[122:125]
	v_mfma_f32_16x16x32_bf16 v[114:117], v[130:133], v[170:173], v[114:117]
	v_mfma_f32_16x16x32_bf16 v[110:113], v[150:153], v[170:173], v[110:113]
	v_mfma_f32_16x16x32_bf16 v[102:105], v[82:85], v[178:181], v[102:105]
	v_mfma_f32_16x16x32_bf16 v[98:101], v[106:109], v[178:181], v[98:101]
	v_mfma_f32_16x16x32_bf16 v[90:93], v[130:133], v[178:181], v[90:93]
	v_mfma_f32_16x16x32_bf16 v[86:89], v[150:153], v[178:181], v[86:89]
	v_mfma_f32_16x16x32_bf16 v[78:81], v[82:85], v[194:197], v[78:81]
	v_mfma_f32_16x16x32_bf16 v[74:77], v[106:109], v[194:197], v[74:77]
	v_mfma_f32_16x16x32_bf16 v[70:73], v[130:133], v[194:197], v[70:73]
	v_mfma_f32_16x16x32_bf16 v[66:69], v[150:153], v[194:197], v[66:69]
	s_setprio 0
	s_setprio 1
	v_mfma_f32_16x16x32_bf16 v[154:157], v[94:97], v[166:169], v[154:157]
	v_mfma_f32_16x16x32_bf16 v[146:149], v[118:121], v[166:169], v[146:149]
	v_mfma_f32_16x16x32_bf16 v[138:141], v[142:145], v[166:169], v[138:141]
	v_mfma_f32_16x16x32_bf16 v[134:137], v[158:161], v[166:169], v[134:137]
	v_mfma_f32_16x16x32_bf16 v[126:129], v[94:97], v[174:177], v[126:129]
	v_mfma_f32_16x16x32_bf16 v[122:125], v[118:121], v[174:177], v[122:125]
	v_mfma_f32_16x16x32_bf16 v[114:117], v[142:145], v[174:177], v[114:117]
	v_mfma_f32_16x16x32_bf16 v[110:113], v[158:161], v[174:177], v[110:113]
	v_mfma_f32_16x16x32_bf16 v[102:105], v[94:97], v[182:185], v[102:105]
	v_mfma_f32_16x16x32_bf16 v[98:101], v[118:121], v[182:185], v[98:101]
	v_mfma_f32_16x16x32_bf16 v[90:93], v[142:145], v[182:185], v[90:93]
	v_mfma_f32_16x16x32_bf16 v[86:89], v[158:161], v[182:185], v[86:89]
	v_mfma_f32_16x16x32_bf16 v[78:81], v[94:97], v[208:211], v[78:81]
	v_mfma_f32_16x16x32_bf16 v[74:77], v[118:121], v[208:211], v[74:77]
	v_mfma_f32_16x16x32_bf16 v[70:73], v[142:145], v[208:211], v[70:73]
	v_mfma_f32_16x16x32_bf16 v[66:69], v[158:161], v[208:211], v[66:69]
	s_setprio 0
	s_barrier
	s_add_i32 s14, s33, s29
	v_lshl_add_u64 v[198:199], v[198:199], 0, s[72:73]
	s_mov_b32 m0, s14
	ds_read_b128 v[162:165], v231 offset:49152
	ds_read_b128 v[166:169], v231 offset:50176
	ds_read_b128 v[170:173], v231 offset:51200
	ds_read_b128 v[174:177], v231 offset:52224
	ds_read_b128 v[178:181], v231 offset:53248
	ds_read_b128 v[182:185], v231 offset:54272
	ds_read_b128 v[194:197], v231 offset:55296
	ds_read_b128 v[208:211], v231 offset:56320
	global_load_lds_dwordx4 v[198:199], off
	s_add_i32 m0, s14, 0x2000
	s_add_u32 s14, s16, 0x160080
	v_lshl_add_u64 v[198:199], v[212:213], 0, s[72:73]
	s_addc_u32 s15, s17, 0
	s_add_i32 s16, s34, s29
	global_load_lds_dwordx4 v[198:199], off
	v_lshl_add_u64 v[198:199], s[14:15], 0, v[188:189]
	s_mov_b32 m0, s16
	s_nop 0
	global_load_lds_dwordx4 v[198:199], off
	v_lshl_add_u64 v[198:199], s[14:15], 0, v[186:187]
	s_add_i32 m0, s16, 0x2000
	s_nop 0
	global_load_lds_dwordx4 v[198:199], off
	v_lshl_add_u64 v[198:199], v[214:215], 0, s[72:73]
	s_mov_b32 m0, s49
	s_nop 0
	global_load_lds_dwordx4 v[198:199], off
	v_lshl_add_u64 v[198:199], v[216:217], 0, s[72:73]
	s_mov_b32 m0, s50
	s_nop 0
	global_load_lds_dwordx4 v[198:199], off
	s_waitcnt vmcnt(8)
	s_waitcnt lgkmcnt(0)
	s_barrier
	s_setprio 1
	s_waitcnt lgkmcnt(0)
	v_mfma_f32_16x16x32_bf16 v[62:65], v[82:85], v[162:165], v[62:65]
	v_mfma_f32_16x16x32_bf16 v[58:61], v[106:109], v[162:165], v[58:61]
	v_mfma_f32_16x16x32_bf16 v[54:57], v[130:133], v[162:165], v[54:57]
	v_mfma_f32_16x16x32_bf16 v[50:53], v[150:153], v[162:165], v[50:53]
	v_mfma_f32_16x16x32_bf16 v[46:49], v[82:85], v[170:173], v[46:49]
	v_mfma_f32_16x16x32_bf16 v[42:45], v[106:109], v[170:173], v[42:45]
	v_mfma_f32_16x16x32_bf16 v[38:41], v[130:133], v[170:173], v[38:41]
	v_mfma_f32_16x16x32_bf16 v[34:37], v[150:153], v[170:173], v[34:37]
	v_mfma_f32_16x16x32_bf16 v[30:33], v[82:85], v[178:181], v[30:33]
	v_mfma_f32_16x16x32_bf16 v[26:29], v[106:109], v[178:181], v[26:29]
	v_mfma_f32_16x16x32_bf16 v[22:25], v[130:133], v[178:181], v[22:25]
	v_mfma_f32_16x16x32_bf16 v[18:21], v[150:153], v[178:181], v[18:21]
	v_mfma_f32_16x16x32_bf16 v[14:17], v[82:85], v[194:197], v[14:17]
	v_mfma_f32_16x16x32_bf16 v[10:13], v[106:109], v[194:197], v[10:13]
	v_mfma_f32_16x16x32_bf16 v[6:9], v[130:133], v[194:197], v[6:9]
	v_mfma_f32_16x16x32_bf16 v[2:5], v[150:153], v[194:197], v[2:5]
	s_setprio 0
	s_setprio 1
	v_mfma_f32_16x16x32_bf16 v[62:65], v[94:97], v[166:169], v[62:65]
	v_mfma_f32_16x16x32_bf16 v[58:61], v[118:121], v[166:169], v[58:61]
	v_mfma_f32_16x16x32_bf16 v[54:57], v[142:145], v[166:169], v[54:57]
	v_mfma_f32_16x16x32_bf16 v[50:53], v[158:161], v[166:169], v[50:53]
	v_mfma_f32_16x16x32_bf16 v[46:49], v[94:97], v[174:177], v[46:49]
	v_mfma_f32_16x16x32_bf16 v[42:45], v[118:121], v[174:177], v[42:45]
	v_mfma_f32_16x16x32_bf16 v[38:41], v[142:145], v[174:177], v[38:41]
	v_mfma_f32_16x16x32_bf16 v[34:37], v[158:161], v[174:177], v[34:37]
	v_mfma_f32_16x16x32_bf16 v[30:33], v[94:97], v[182:185], v[30:33]
	v_mfma_f32_16x16x32_bf16 v[26:29], v[118:121], v[182:185], v[26:29]
	v_mfma_f32_16x16x32_bf16 v[22:25], v[142:145], v[182:185], v[22:25]
	v_mfma_f32_16x16x32_bf16 v[18:21], v[158:161], v[182:185], v[18:21]
	v_mfma_f32_16x16x32_bf16 v[14:17], v[94:97], v[208:211], v[14:17]
	v_mfma_f32_16x16x32_bf16 v[10:13], v[118:121], v[208:211], v[10:13]
	v_mfma_f32_16x16x32_bf16 v[6:9], v[142:145], v[208:211], v[6:9]
	v_mfma_f32_16x16x32_bf16 v[2:5], v[158:161], v[208:211], v[2:5]
	s_setprio 0
	s_barrier
	s_add_i32 s22, s22, 2
	s_add_u32 s3, s3, 0x100
	s_addc_u32 s18, s18, 0
	s_cmpk_gt_u32 s22, 0x55
	s_mov_b64 s[14:15], s[0:1]
	s_cbranch_scc0 .LBB0_765
	s_and_b64 vcc, exec, s[46:47]
	s_cbranch_vccz .LBB0_768
	s_barrier
